# P1 epilogue: 8 rowsq loads issued together; P6 epilogue: redundant v_max canonicalisations removed
# speedup vs baseline: 1.0046x; 1.0046x over previous
; __device__ __forceinline__ unsigned cvt_pk_bf16(float lo, float hi) { unsigned r; asm volatile("v_cvt_pk_bf16_f32 %0, %1, %2" : "=v"(r) : "v"(lo), "v"(hi)); return r; }
;     __device__ __forceinline__ void operator()(const f32x4 (&acc)[2][2][4][2], const Unit& u, int wr, int wc, int fr, int fq) const {
;         const int row0 = u.pm * BM + wr * 64 + fr;
;         float rs[2][4];
; #pragma unroll
;         for (int ai = 0; ai < 2; ++ai)
; #pragma unroll
;             for (int m = 0; m < 4; ++m) rs[ai][m] = rsqrtf(rowsq[row0 + ai * HALF + m * 16] * (1.0f / 2048.0f) + 1e-6f);
;         if (u.pn == small_pn) {
;             if (wc == 0) {
; #pragma unroll
;                 for (int ai = 0; ai < 2; ++ai)
; #pragma unroll
;                     for (int m = 0; m < 4; ++m) { float* p = small + (size_t)(row0 + ai * HALF + m * 16) * 32 + 8 * fq;
;                         *(f32x4*)p = acc[ai][0][m][0] * rs[ai][m]; *(f32x4*)(p + 4) = acc[ai][0][m][1] * rs[ai][m]; }
;             }
;             return;
;         }
;         const int col0 = u.pn * BM + wc * 32 + 8 * fq;
; #pragma unroll
;         for (int ai = 0; ai < 2; ++ai)
; #pragma unroll
;             for (int m = 0; m < 4; ++m) { bf16_t* rowp = O + (size_t)(row0 + ai * HALF + m * 16) * ldc + col0;
; #pragma unroll
;                 for (int bj = 0; bj < 2; ++bj) { const f32x4 v0 = acc[ai][bj][m][0] * rs[ai][m], v1 = acc[ai][bj][m][1] * rs[ai][m];
;                     u32x4 w; w.x = cvt_pk_bf16(v0[0], v0[1]); w.y = cvt_pk_bf16(v0[2], v0[3]); w.z = cvt_pk_bf16(v1[0], v1[1]); w.w = cvt_pk_bf16(v1[2], v1[3]);
;                     *(u32x4*)(rowp + bj * HALF) = w; } }
.LBB0_1170:
	v_lshl_add_u32 v146, s27, 8, v1
	v_ashrrev_i32_e32 v147, 31, v146
	v_lshl_add_u64 v[174:175], v[146:147], 2, s[8:9]
	global_load_dword v144, v[174:175], off
	global_load_dword v148, v[174:175], off offset:64
	global_load_dword v152, v[174:175], off offset:128
	global_load_dword v244, v[174:175], off offset:192
	global_load_dword v159, v[174:175], off offset:512
	global_load_dword v245, v[174:175], off offset:576
	global_load_dword v246, v[174:175], off offset:640
	global_load_dword v247, v[174:175], off offset:704
	v_or_b32_e32 v150, 16, v146
	v_ashrrev_i32_e32 v151, 31, v150
	v_or_b32_e32 v156, 32, v146
	v_ashrrev_i32_e32 v157, 31, v156
	v_or_b32_e32 v160, 48, v146
	v_ashrrev_i32_e32 v161, 31, v160
	v_add_u32_e32 v166, 0xa0, v146
	v_add_u32_e32 v170, 0xb0, v146
	v_ashrrev_i32_e32 v167, 31, v166
	v_ashrrev_i32_e32 v171, 31, v170
	v_add_u32_e32 v154, 0x80, v146
	v_ashrrev_i32_e32 v155, 31, v154
	v_add_u32_e32 v162, 0x90, v146
	v_ashrrev_i32_e32 v163, 31, v162
	s_mov_b64 s[36:37], -1
	s_cmp_lg_u32 s54, 25
	s_waitcnt vmcnt(0)
	v_fmamk_f32 v144, v144, 0x3a000000, v232
	v_cmp_gt_f32_e32 vcc, s22, v144
	v_mul_f32_e32 v165, 0x4b800000, v144
	s_nop 0
	v_cndmask_b32_e32 v144, v144, v165, vcc
	v_rsq_f32_e32 v144, v144
	s_nop 0
	v_mul_f32_e32 v165, 0x45800000, v144
	v_cndmask_b32_e32 v144, v144, v165, vcc
	v_fmamk_f32 v148, v148, 0x3a000000, v232
	v_cmp_gt_f32_e32 vcc, s22, v148
	v_mul_f32_e32 v165, 0x4b800000, v148
	s_nop 0
	v_cndmask_b32_e32 v148, v148, v165, vcc
	v_rsq_f32_e32 v148, v148
	s_nop 0
	v_mul_f32_e32 v165, 0x45800000, v148
	v_cndmask_b32_e32 v148, v148, v165, vcc
	v_fmamk_f32 v152, v152, 0x3a000000, v232
	v_cmp_gt_f32_e32 vcc, s22, v152
	v_mul_f32_e32 v165, 0x4b800000, v152
	s_nop 0
	v_cndmask_b32_e32 v152, v152, v165, vcc
	v_rsq_f32_e32 v152, v152
	s_nop 0
	v_mul_f32_e32 v165, 0x45800000, v152
	v_cndmask_b32_e32 v152, v152, v165, vcc
	v_fmamk_f32 v244, v244, 0x3a000000, v232
	v_cmp_gt_f32_e32 vcc, s22, v244
	v_mul_f32_e32 v165, 0x4b800000, v244
	s_nop 0
	v_cndmask_b32_e32 v244, v244, v165, vcc
	v_rsq_f32_e32 v244, v244
	s_nop 0
	v_mul_f32_e32 v165, 0x45800000, v244
	v_cndmask_b32_e32 v158, v244, v165, vcc
	v_fmamk_f32 v159, v159, 0x3a000000, v232
	v_cmp_gt_f32_e32 vcc, s22, v159
	v_mul_f32_e32 v165, 0x4b800000, v159
	s_nop 0
	v_cndmask_b32_e32 v159, v159, v165, vcc
	v_rsq_f32_e32 v159, v159
	s_nop 0
	v_mul_f32_e32 v165, 0x45800000, v159
	v_cndmask_b32_e32 v164, v159, v165, vcc
	v_fmamk_f32 v245, v245, 0x3a000000, v232
	v_cmp_gt_f32_e32 vcc, s22, v245
	v_mul_f32_e32 v165, 0x4b800000, v245
	s_nop 0
	v_cndmask_b32_e32 v245, v245, v165, vcc
	v_rsq_f32_e32 v245, v245
	s_nop 0
	v_mul_f32_e32 v165, 0x45800000, v245
	v_cndmask_b32_e32 v168, v245, v165, vcc
	v_fmamk_f32 v246, v246, 0x3a000000, v232
	v_cmp_gt_f32_e32 vcc, s22, v246
	v_mul_f32_e32 v165, 0x4b800000, v246
	s_nop 0
	v_cndmask_b32_e32 v246, v246, v165, vcc
	v_rsq_f32_e32 v246, v246
	s_nop 0
	v_mul_f32_e32 v165, 0x45800000, v246
	v_cndmask_b32_e32 v172, v246, v165, vcc
	v_fmamk_f32 v247, v247, 0x3a000000, v232
	v_cmp_gt_f32_e32 vcc, s22, v247
	v_mul_f32_e32 v165, 0x4b800000, v247
	s_nop 0
	v_cndmask_b32_e32 v247, v247, v165, vcc
	v_rsq_f32_e32 v247, v247
	s_nop 0
	v_mul_f32_e32 v165, 0x45800000, v247
	v_cndmask_b32_e32 v174, v247, v165, vcc
	s_cbranch_scc0 .LBB0_1172
	v_lshl_or_b32 v178, s54, 8, v149
	v_ashrrev_i32_e32 v179, 31, v178
	v_mov_b64_e32 v[176:177], s[6:7]
	v_mad_i64_i32 v[182:183], s[26:27], v146, s23, v[176:177]
	v_lshlrev_b64 v[178:179], 1, v[178:179]
	v_lshl_add_u64 v[186:187], v[182:183], 0, v[178:179]
	v_pk_mul_f32 v[182:183], v[80:81], v[144:145] op_sel_hi:[1,0]
	v_pk_mul_f32 v[184:185], v[82:83], v[144:145] op_sel_hi:[1,0]
	v_cvt_pk_bf16_f32 v182, v182, v183
	v_pk_mul_f32 v[188:189], v[78:79], v[144:145] op_sel_hi:[1,0]
	v_cvt_pk_bf16_f32 v183, v184, v185
	v_pk_mul_f32 v[190:191], v[76:77], v[144:145] op_sel_hi:[1,0]
	v_pk_mul_f32 v[130:131], v[130:131], v[144:145] op_sel_hi:[1,0]
	v_cvt_pk_bf16_f32 v184, v190, v191
	v_cvt_pk_bf16_f32 v185, v188, v189
	global_store_dwordx4 v[186:187], v[182:185], off
	v_pk_mul_f32 v[128:129], v[128:129], v[144:145] op_sel_hi:[1,0]
	v_pk_mul_f32 v[122:123], v[122:123], v[148:149] op_sel_hi:[1,0]
	v_pk_mul_f32 v[182:183], v[126:127], v[144:145] op_sel_hi:[1,0]
	v_pk_mul_f32 v[126:127], v[124:125], v[144:145] op_sel_hi:[1,0]
	v_cvt_pk_bf16_f32 v124, v128, v129
	v_cvt_pk_bf16_f32 v125, v130, v131
	v_pk_mul_f32 v[130:131], v[62:63], v[148:149] op_sel_hi:[1,0]
	v_cvt_pk_bf16_f32 v126, v126, v127
	v_cvt_pk_bf16_f32 v127, v182, v183
	global_store_dwordx4 v[186:187], v[124:127], off offset:256
	v_pk_mul_f32 v[182:183], v[60:61], v[148:149] op_sel_hi:[1,0]
	v_pk_mul_f32 v[120:121], v[120:121], v[148:149] op_sel_hi:[1,0]
	v_mad_i64_i32 v[124:125], s[26:27], v150, s23, v[176:177]
	v_lshl_add_u64 v[128:129], v[124:125], 0, v[178:179]
	v_pk_mul_f32 v[124:125], v[64:65], v[148:149] op_sel_hi:[1,0]
	v_pk_mul_f32 v[126:127], v[66:67], v[148:149] op_sel_hi:[1,0]
	v_cvt_pk_bf16_f32 v124, v124, v125
	v_pk_mul_f32 v[114:115], v[114:115], v[152:153] op_sel_hi:[1,0]
	v_cvt_pk_bf16_f32 v125, v126, v127
	v_cvt_pk_bf16_f32 v126, v182, v183
	v_cvt_pk_bf16_f32 v127, v130, v131
	global_store_dwordx4 v[128:129], v[124:127], off
	v_pk_mul_f32 v[112:113], v[112:113], v[152:153] op_sel_hi:[1,0]
	v_pk_mul_f32 v[106:107], v[106:107], v[158:159] op_sel_hi:[1,0]
	v_pk_mul_f32 v[124:125], v[118:119], v[148:149] op_sel_hi:[1,0]
	v_pk_mul_f32 v[118:119], v[116:117], v[148:149] op_sel_hi:[1,0]
	v_cvt_pk_bf16_f32 v116, v120, v121
	v_cvt_pk_bf16_f32 v117, v122, v123
	v_pk_mul_f32 v[122:123], v[54:55], v[152:153] op_sel_hi:[1,0]
	v_cvt_pk_bf16_f32 v118, v118, v119
; __device__ __forceinline__ unsigned cvt_pk_bf16(float lo, float hi) { unsigned r; asm volatile("v_cvt_pk_bf16_f32 %0, %1, %2" : "=v"(r) : "v"(lo), "v"(hi)); return r; }
;     __device__ __forceinline__ void operator()(const f32x4 (&acc)[2][2][4][2], const Unit& u, int wr, int wc, int fr, int fq) const {
;     ...
;             for (int m = 0; m < 4; ++m) { bf16_t* rowp = O + (size_t)(row0 + ai * HALF + m * 16) * ldc + col0;
; #pragma unroll
;                 for (int bj = 0; bj < 2; ++bj) { const f32x4 v0 = acc[ai][bj][m][0] * rs[ai][m], v1 = acc[ai][bj][m][1] * rs[ai][m];
;                     u32x4 w; w.x = cvt_pk_bf16(v0[0], v0[1]); w.y = cvt_pk_bf16(v0[2], v0[3]); w.z = cvt_pk_bf16(v1[0], v1[1]); w.w = cvt_pk_bf16(v1[2], v1[3]);
;                     *(u32x4*)(rowp + bj * HALF) = w; } }
	v_cvt_pk_bf16_f32 v119, v124, v125
	global_store_dwordx4 v[128:129], v[116:119], off offset:256
	v_pk_mul_f32 v[124:125], v[52:53], v[152:153] op_sel_hi:[1,0]
	v_pk_mul_f32 v[104:105], v[104:105], v[158:159] op_sel_hi:[1,0]
	v_mad_i64_i32 v[116:117], s[26:27], v156, s23, v[176:177]
	v_lshl_add_u64 v[120:121], v[116:117], 0, v[178:179]
	v_pk_mul_f32 v[116:117], v[56:57], v[152:153] op_sel_hi:[1,0]
	v_pk_mul_f32 v[118:119], v[58:59], v[152:153] op_sel_hi:[1,0]
	v_cvt_pk_bf16_f32 v116, v116, v117
	v_pk_mul_f32 v[98:99], v[98:99], v[164:165] op_sel_hi:[1,0]
	v_cvt_pk_bf16_f32 v117, v118, v119
	v_cvt_pk_bf16_f32 v118, v124, v125
	v_cvt_pk_bf16_f32 v119, v122, v123
	global_store_dwordx4 v[120:121], v[116:119], off
	v_pk_mul_f32 v[96:97], v[96:97], v[164:165] op_sel_hi:[1,0]
	v_pk_mul_f32 v[90:91], v[90:91], v[168:169] op_sel_hi:[1,0]
	v_pk_mul_f32 v[116:117], v[110:111], v[152:153] op_sel_hi:[1,0]
	v_pk_mul_f32 v[110:111], v[108:109], v[152:153] op_sel_hi:[1,0]
	v_cvt_pk_bf16_f32 v108, v112, v113
	v_cvt_pk_bf16_f32 v109, v114, v115
	v_pk_mul_f32 v[114:115], v[38:39], v[158:159] op_sel_hi:[1,0]
	v_cvt_pk_bf16_f32 v110, v110, v111
	v_cvt_pk_bf16_f32 v111, v116, v117
	global_store_dwordx4 v[120:121], v[108:111], off offset:256
	v_pk_mul_f32 v[116:117], v[36:37], v[158:159] op_sel_hi:[1,0]
	v_pk_mul_f32 v[88:89], v[88:89], v[168:169] op_sel_hi:[1,0]
	v_mad_i64_i32 v[108:109], s[26:27], v160, s23, v[176:177]
	v_lshl_add_u64 v[112:113], v[108:109], 0, v[178:179]
	v_pk_mul_f32 v[108:109], v[44:45], v[158:159] op_sel_hi:[1,0]
	v_pk_mul_f32 v[110:111], v[46:47], v[158:159] op_sel_hi:[1,0]
	v_cvt_pk_bf16_f32 v108, v108, v109
	v_pk_mul_f32 v[74:75], v[74:75], v[172:173] op_sel_hi:[1,0]
	v_cvt_pk_bf16_f32 v109, v110, v111
	v_cvt_pk_bf16_f32 v110, v116, v117
	v_cvt_pk_bf16_f32 v111, v114, v115
	global_store_dwordx4 v[112:113], v[108:111], off
	v_pk_mul_f32 v[72:73], v[72:73], v[172:173] op_sel_hi:[1,0]
	v_pk_mul_f32 v[50:51], v[50:51], v[174:175] op_sel_hi:[1,0]
	v_pk_mul_f32 v[108:109], v[102:103], v[158:159] op_sel_hi:[1,0]
	v_pk_mul_f32 v[102:103], v[100:101], v[158:159] op_sel_hi:[1,0]
	v_cvt_pk_bf16_f32 v100, v104, v105
	v_cvt_pk_bf16_f32 v101, v106, v107
	v_pk_mul_f32 v[106:107], v[30:31], v[164:165] op_sel_hi:[1,0]
	v_cvt_pk_bf16_f32 v102, v102, v103
	v_cvt_pk_bf16_f32 v103, v108, v109
	global_store_dwordx4 v[112:113], v[100:103], off offset:256
	v_pk_mul_f32 v[108:109], v[28:29], v[164:165] op_sel_hi:[1,0]
	v_pk_mul_f32 v[48:49], v[48:49], v[174:175] op_sel_hi:[1,0]
	v_mad_i64_i32 v[100:101], s[26:27], v154, s23, v[176:177]
	v_lshl_add_u64 v[104:105], v[100:101], 0, v[178:179]
	v_pk_mul_f32 v[100:101], v[32:33], v[164:165] op_sel_hi:[1,0]
	v_pk_mul_f32 v[102:103], v[34:35], v[164:165] op_sel_hi:[1,0]
	v_cvt_pk_bf16_f32 v100, v100, v101
	s_mov_b64 s[36:37], 0
	v_cvt_pk_bf16_f32 v101, v102, v103
	v_cvt_pk_bf16_f32 v102, v108, v109
	v_cvt_pk_bf16_f32 v103, v106, v107
	global_store_dwordx4 v[104:105], v[100:103], off
	s_nop 1
	v_pk_mul_f32 v[100:101], v[94:95], v[164:165] op_sel_hi:[1,0]
	v_pk_mul_f32 v[94:95], v[92:93], v[164:165] op_sel_hi:[1,0]
	v_cvt_pk_bf16_f32 v92, v96, v97
	v_cvt_pk_bf16_f32 v93, v98, v99
	v_pk_mul_f32 v[98:99], v[22:23], v[168:169] op_sel_hi:[1,0]
	v_cvt_pk_bf16_f32 v94, v94, v95
	v_cvt_pk_bf16_f32 v95, v100, v101
	global_store_dwordx4 v[104:105], v[92:95], off offset:256
	v_pk_mul_f32 v[100:101], v[20:21], v[168:169] op_sel_hi:[1,0]
	s_nop 0
	v_mad_i64_i32 v[92:93], s[26:27], v162, s23, v[176:177]
	v_lshl_add_u64 v[96:97], v[92:93], 0, v[178:179]
	v_pk_mul_f32 v[92:93], v[24:25], v[168:169] op_sel_hi:[1,0]
	v_pk_mul_f32 v[94:95], v[26:27], v[168:169] op_sel_hi:[1,0]
	v_cvt_pk_bf16_f32 v92, v92, v93
	s_nop 0
	v_cvt_pk_bf16_f32 v93, v94, v95
	v_cvt_pk_bf16_f32 v94, v100, v101
	v_cvt_pk_bf16_f32 v95, v98, v99
	global_store_dwordx4 v[96:97], v[92:95], off
	s_nop 1
	v_pk_mul_f32 v[92:93], v[86:87], v[168:169] op_sel_hi:[1,0]
	v_pk_mul_f32 v[86:87], v[84:85], v[168:169] op_sel_hi:[1,0]
	v_cvt_pk_bf16_f32 v84, v88, v89
	v_cvt_pk_bf16_f32 v85, v90, v91
	v_pk_mul_f32 v[90:91], v[14:15], v[172:173] op_sel_hi:[1,0]
	v_cvt_pk_bf16_f32 v86, v86, v87
	v_cvt_pk_bf16_f32 v87, v92, v93
	global_store_dwordx4 v[96:97], v[84:87], off offset:256
	v_pk_mul_f32 v[92:93], v[12:13], v[172:173] op_sel_hi:[1,0]
	s_nop 0
	v_mad_i64_i32 v[84:85], s[26:27], v166, s23, v[176:177]
	v_lshl_add_u64 v[88:89], v[84:85], 0, v[178:179]
	v_pk_mul_f32 v[84:85], v[16:17], v[172:173] op_sel_hi:[1,0]
	v_pk_mul_f32 v[86:87], v[18:19], v[172:173] op_sel_hi:[1,0]
	v_cvt_pk_bf16_f32 v84, v84, v85
	s_nop 0
	v_cvt_pk_bf16_f32 v85, v86, v87
	v_cvt_pk_bf16_f32 v86, v92, v93
	v_cvt_pk_bf16_f32 v87, v90, v91
	global_store_dwordx4 v[88:89], v[84:87], off
	s_nop 1
	v_pk_mul_f32 v[84:85], v[70:71], v[172:173] op_sel_hi:[1,0]
	v_pk_mul_f32 v[70:71], v[68:69], v[172:173] op_sel_hi:[1,0]
	v_cvt_pk_bf16_f32 v68, v72, v73
	v_cvt_pk_bf16_f32 v69, v74, v75
	v_pk_mul_f32 v[74:75], v[6:7], v[174:175] op_sel_hi:[1,0]
	v_cvt_pk_bf16_f32 v70, v70, v71
	v_cvt_pk_bf16_f32 v71, v84, v85
	global_store_dwordx4 v[88:89], v[68:71], off offset:256
	v_pk_mul_f32 v[84:85], v[4:5], v[174:175] op_sel_hi:[1,0]
	s_nop 0
	v_mad_i64_i32 v[68:69], s[26:27], v170, s23, v[176:177]
	v_lshl_add_u64 v[72:73], v[68:69], 0, v[178:179]
	v_pk_mul_f32 v[68:69], v[8:9], v[174:175] op_sel_hi:[1,0]
	v_pk_mul_f32 v[70:71], v[10:11], v[174:175] op_sel_hi:[1,0]
	v_cvt_pk_bf16_f32 v68, v68, v69
	s_nop 0
	v_cvt_pk_bf16_f32 v69, v70, v71
	v_cvt_pk_bf16_f32 v70, v84, v85
	v_cvt_pk_bf16_f32 v71, v74, v75
	global_store_dwordx4 v[72:73], v[68:71], off
	s_nop 1
	v_pk_mul_f32 v[68:69], v[42:43], v[174:175] op_sel_hi:[1,0]
	v_pk_mul_f32 v[42:43], v[40:41], v[174:175] op_sel_hi:[1,0]
	v_cvt_pk_bf16_f32 v40, v48, v49
	v_cvt_pk_bf16_f32 v41, v50, v51
	s_nop 0
	v_cvt_pk_bf16_f32 v42, v42, v43
	v_cvt_pk_bf16_f32 v43, v68, v69
	global_store_dwordx4 v[72:73], v[40:43], off offset:256

; __device__ __forceinline__ unsigned cvt_pk_bf16(float lo, float hi) { unsigned r; asm volatile("v_cvt_pk_bf16_f32 %0, %1, %2" : "=v"(r) : "v"(lo), "v"(hi)); return r; }
;     __device__ __forceinline__ void operator()(const f32x4 (&acc)[2][2][4][2], const Unit& u, int wr, int wc, int fr, int fq) const {
;     ...
;             for (int m = 0; m < 4; ++m) { bf16_t* rowp = O + (size_t)(row0 + ai * HALF + m * 16) * ldc + col0;
;                 const float r2 = 1.0f / (rowsq[row0 + ai * HALF + m * 16] * (1.0f / 2048.0f) + 1e-6f);
; #pragma unroll
;                 for (int bj = 0; bj < 2; ++bj) { f32x4 v0 = acc[ai][bj][m][0], v1 = acc[ai][bj][m][1];
; #pragma unroll
;                     for (int j = 0; j < 4; ++j) { const float a = fmaxf(v0[j], 0.f), b = fmaxf(v1[j], 0.f); v0[j] = a * a * r2; v1[j] = b * b * r2; }
;                     u32x4 w; w.x = cvt_pk_bf16(v0[0], v0[1]); w.y = cvt_pk_bf16(v0[2], v0[3]); w.z = cvt_pk_bf16(v1[0], v1[1]); w.w = cvt_pk_bf16(v1[2], v1[3]);
;                     __builtin_nontemporal_store(w, (u32x4*)(rowp + bj * HALF)); } }
.LBB0_2107:
	v_lshl_add_u32 v144, s30, 8, v1
	v_ashrrev_i32_e32 v145, 31, v144
	v_lshl_add_u64 v[142:143], v[144:145], 2, s[10:11]
	global_load_dword v149, v[142:143], off
	v_lshl_or_b32 v150, s27, 8, v147
	v_ashrrev_i32_e32 v151, 31, v150
	v_max_f32_e32 v153, 0, v116
	v_max_f32_e32 v155, 0, v118
	v_max_f32_e32 v152, 0, v124
	v_max_f32_e32 v154, 0, v117
	v_max_f32_e32 v156, 0, v119
	v_lshlrev_b64 v[118:119], 1, v[150:151]
	v_mul_f32_e32 v151, v153, v153
	v_mul_f32_e32 v153, v155, v155
	v_lshlrev_b64 v[116:117], 14, v[144:145]
	v_mul_f32_e32 v145, v152, v152
	v_mul_f32_e32 v152, v154, v154
	v_mul_f32_e32 v154, v156, v156
	v_max_f32_e32 v128, 0, v128
	v_max_f32_e32 v129, 0, v129
	v_max_f32_e32 v130, 0, v130
	v_max_f32_e32 v131, 0, v131
	v_max_f32_e32 v120, 0, v120
	v_max_f32_e32 v121, 0, v121
	v_max_f32_e32 v125, 0, v125
	v_max_f32_e32 v126, 0, v126
	v_max_f32_e32 v127, 0, v127
	v_max_f32_e32 v122, 0, v122
	v_max_f32_e32 v123, 0, v123
	v_mul_f32_e32 v128, v128, v128
	v_mul_f32_e32 v129, v129, v129
	v_mul_f32_e32 v130, v130, v130
	v_mul_f32_e32 v131, v131, v131
	v_mul_f32_e32 v120, v120, v120
	v_mul_f32_e32 v121, v121, v121
	v_lshl_add_u64 v[116:117], s[8:9], 0, v[116:117]
	v_or_b32_e32 v124, 16, v144
	v_mul_f32_e32 v150, v125, v125
	v_mul_f32_e32 v126, v126, v126
	v_mul_f32_e32 v127, v127, v127
	v_mul_f32_e32 v122, v122, v122
	v_mul_f32_e32 v123, v123, v123
	v_lshl_add_u64 v[116:117], v[116:117], 0, v[118:119]
	v_ashrrev_i32_e32 v125, 31, v124
	v_max_f32_e32 v100, 0, v100
	v_max_f32_e32 v101, 0, v101
	v_max_f32_e32 v108, 0, v108
	v_max_f32_e32 v109, 0, v109
	v_max_f32_e32 v112, 0, v112
	v_max_f32_e32 v113, 0, v113
	v_max_f32_e32 v114, 0, v114
	s_waitcnt vmcnt(0)
	v_fmamk_f32 v149, v149, 0x3a000000, v232
	v_div_scale_f32 v155, s[26:27], v149, v149, 1.0
	v_rcp_f32_e32 v156, v155
	v_div_scale_f32 v157, vcc, 1.0, v149, 1.0
	v_max_f32_e32 v110, 0, v110
	v_fma_f32 v158, -v155, v156, 1.0
	v_fmac_f32_e32 v156, v158, v156
	v_mul_f32_e32 v158, v157, v156
	v_fma_f32 v159, -v155, v158, v157
	v_fmac_f32_e32 v158, v159, v156
	v_fma_f32 v155, -v155, v158, v157
	v_div_fmas_f32 v155, v155, v156, v158
	v_div_fixup_f32 v149, v155, v149, 1.0
	v_mul_f32_e32 v128, v128, v149
	v_mul_f32_e32 v129, v129, v149
	v_mul_f32_e32 v130, v130, v149
	v_mul_f32_e32 v131, v131, v149
	v_mul_f32_e32 v155, v120, v149
	v_mul_f32_e32 v156, v121, v149
	v_cvt_pk_bf16_f32 v120, v128, v129
	v_cvt_pk_bf16_f32 v121, v130, v131
	v_mul_f32_e32 v145, v145, v149
	v_mul_f32_e32 v150, v150, v149
	v_mul_f32_e32 v126, v126, v149
	v_mul_f32_e32 v127, v127, v149
	v_mul_f32_e32 v157, v122, v149
	v_mul_f32_e32 v158, v123, v149
	v_cvt_pk_bf16_f32 v122, v145, v150
	v_cvt_pk_bf16_f32 v123, v126, v127
	global_store_dwordx4 v[116:117], v[120:123], off nt
	v_mul_f32_e32 v151, v151, v149
	v_mul_f32_e32 v152, v152, v149
	v_cvt_pk_bf16_f32 v120, v155, v156
	v_cvt_pk_bf16_f32 v121, v157, v158
	v_mul_f32_e32 v153, v153, v149
	v_mul_f32_e32 v149, v154, v149
	v_cvt_pk_bf16_f32 v122, v151, v152
	v_cvt_pk_bf16_f32 v123, v153, v149
	global_store_dwordx4 v[116:117], v[120:123], off offset:256 nt
	v_mul_f32_e32 v126, v100, v100
	v_mul_f32_e32 v128, v101, v101
	v_lshl_add_u64 v[120:121], v[124:125], 2, s[10:11]
	global_load_dword v120, v[120:121], off
	v_lshlrev_b64 v[100:101], 14, v[124:125]
	v_lshl_add_u64 v[100:101], s[8:9], 0, v[100:101]
	v_mul_f32_e32 v122, v108, v108
	v_mul_f32_e32 v123, v109, v109
	v_lshl_add_u64 v[108:109], v[100:101], 0, v[118:119]
	v_max_f32_e32 v115, 0, v115
	v_max_f32_e32 v111, 0, v111
	v_max_f32_e32 v121, 0, v104
	v_max_f32_e32 v105, 0, v105
	v_max_f32_e32 v106, 0, v106
	v_max_f32_e32 v102, 0, v102
	v_max_f32_e32 v107, 0, v107
	v_max_f32_e32 v103, 0, v103
	v_mul_f32_e32 v112, v112, v112
	v_or_b32_e32 v104, 32, v144
	v_mul_f32_e32 v113, v113, v113
	v_mul_f32_e32 v114, v114, v114
	v_mul_f32_e32 v110, v110, v110
	v_mul_f32_e32 v115, v115, v115
	v_mul_f32_e32 v111, v111, v111
	v_mul_f32_e32 v121, v121, v121
	v_mul_f32_e32 v127, v105, v105
	v_mul_f32_e32 v129, v106, v106
	v_mul_f32_e32 v102, v102, v102
	v_mul_f32_e32 v130, v107, v107
	v_mul_f32_e32 v103, v103, v103
	v_ashrrev_i32_e32 v105, 31, v104
	v_lshl_add_u64 v[106:107], v[104:105], 2, s[10:11]
	v_max_f32_e32 v84, 0, v84
	v_max_f32_e32 v85, 0, v85
	v_max_f32_e32 v92, 0, v92
	v_max_f32_e32 v93, 0, v93
	v_max_f32_e32 v96, 0, v96
	v_max_f32_e32 v97, 0, v97
	v_max_f32_e32 v98, 0, v98
	v_max_f32_e32 v94, 0, v94
	v_max_f32_e32 v99, 0, v99
	v_max_f32_e32 v95, 0, v95
	v_max_f32_e32 v89, 0, v89
	v_max_f32_e32 v90, 0, v90
	v_max_f32_e32 v86, 0, v86
	v_max_f32_e32 v91, 0, v91
	v_max_f32_e32 v87, 0, v87
	v_mul_f32_e32 v96, v96, v96
	v_mul_f32_e32 v97, v97, v97
	v_mul_f32_e32 v98, v98, v98
	v_mul_f32_e32 v94, v94, v94
	v_mul_f32_e32 v99, v99, v99
	v_mul_f32_e32 v95, v95, v95
	v_mul_f32_e32 v86, v86, v86
	v_mul_f32_e32 v87, v87, v87
	v_max_f32_e32 v68, 0, v68
	v_max_f32_e32 v69, 0, v69
	v_max_f32_e32 v72, 0, v72
	v_max_f32_e32 v73, 0, v73
	s_waitcnt vmcnt(0)
; __device__ __forceinline__ unsigned cvt_pk_bf16(float lo, float hi) { unsigned r; asm volatile("v_cvt_pk_bf16_f32 %0, %1, %2" : "=v"(r) : "v"(lo), "v"(hi)); return r; }
;     __device__ __forceinline__ void operator()(const f32x4 (&acc)[2][2][4][2], const Unit& u, int wr, int wc, int fr, int fq) const {
;     ...
;             for (int m = 0; m < 4; ++m) { bf16_t* rowp = O + (size_t)(row0 + ai * HALF + m * 16) * ldc + col0;
;                 const float r2 = 1.0f / (rowsq[row0 + ai * HALF + m * 16] * (1.0f / 2048.0f) + 1e-6f);
; #pragma unroll
;                 for (int bj = 0; bj < 2; ++bj) { f32x4 v0 = acc[ai][bj][m][0], v1 = acc[ai][bj][m][1];
; #pragma unroll
;                     for (int j = 0; j < 4; ++j) { const float a = fmaxf(v0[j], 0.f), b = fmaxf(v1[j], 0.f); v0[j] = a * a * r2; v1[j] = b * b * r2; }
;                     u32x4 w; w.x = cvt_pk_bf16(v0[0], v0[1]); w.y = cvt_pk_bf16(v0[2], v0[3]); w.z = cvt_pk_bf16(v1[0], v1[1]); w.w = cvt_pk_bf16(v1[2], v1[3]);
;                     __builtin_nontemporal_store(w, (u32x4*)(rowp + bj * HALF)); } }
	v_fmamk_f32 v120, v120, 0x3a000000, v232
	v_div_scale_f32 v124, s[26:27], v120, v120, 1.0
	v_rcp_f32_e32 v125, v124
	v_div_scale_f32 v100, vcc, 1.0, v120, 1.0
	v_fma_f32 v101, -v124, v125, 1.0
	v_fmac_f32_e32 v125, v101, v125
	v_mul_f32_e32 v101, v100, v125
	v_fma_f32 v131, -v124, v101, v100
	v_fmac_f32_e32 v101, v131, v125
	v_fma_f32 v100, -v124, v101, v100
	v_div_fmas_f32 v100, v100, v125, v101
	v_div_fixup_f32 v100, v100, v120, 1.0
	v_mul_f32_e32 v101, v112, v100
	v_mul_f32_e32 v112, v122, v100
	v_mul_f32_e32 v113, v113, v100
	v_mul_f32_e32 v120, v123, v100
	v_mul_f32_e32 v114, v114, v100
	v_mul_f32_e32 v110, v110, v100
	v_mul_f32_e32 v115, v115, v100
	v_mul_f32_e32 v111, v111, v100
	v_mul_f32_e32 v121, v121, v100
	v_mul_f32_e32 v122, v126, v100
	v_mul_f32_e32 v123, v127, v100
	v_mul_f32_e32 v124, v128, v100
	v_mul_f32_e32 v125, v129, v100
	v_mul_f32_e32 v126, v102, v100
	v_mul_f32_e32 v127, v130, v100
	v_mul_f32_e32 v128, v103, v100
	v_cvt_pk_bf16_f32 v100, v101, v113
	v_cvt_pk_bf16_f32 v101, v114, v115
	v_cvt_pk_bf16_f32 v102, v112, v120
	v_cvt_pk_bf16_f32 v103, v110, v111
	global_store_dwordx4 v[108:109], v[100:103], off nt
	v_mul_f32_e32 v110, v91, v91
	s_nop 0
	v_cvt_pk_bf16_f32 v100, v121, v123
	v_cvt_pk_bf16_f32 v101, v125, v127
	v_cvt_pk_bf16_f32 v102, v122, v124
	v_cvt_pk_bf16_f32 v103, v126, v128
	global_store_dwordx4 v[108:109], v[100:103], off offset:256 nt
	global_load_dword v100, v[106:107], off
	v_mul_f32_e32 v106, v84, v84
	v_mul_f32_e32 v108, v85, v85
	v_lshlrev_b64 v[84:85], 14, v[104:105]
	v_lshl_add_u64 v[84:85], s[8:9], 0, v[84:85]
	v_mul_f32_e32 v102, v92, v92
	v_mul_f32_e32 v103, v93, v93
	v_lshl_add_u64 v[92:93], v[84:85], 0, v[118:119]
	v_max_f32_e32 v101, 0, v88
	v_or_b32_e32 v88, 48, v144
	v_mul_f32_e32 v101, v101, v101
	v_mul_f32_e32 v107, v89, v89
	v_mul_f32_e32 v109, v90, v90
	v_ashrrev_i32_e32 v89, 31, v88
	v_lshl_add_u64 v[90:91], v[88:89], 2, s[10:11]
	v_max_f32_e32 v80, 0, v80
	v_max_f32_e32 v76, 0, v76
	v_max_f32_e32 v81, 0, v81
	v_max_f32_e32 v77, 0, v77
	v_max_f32_e32 v82, 0, v82
	v_max_f32_e32 v78, 0, v78
	v_max_f32_e32 v83, 0, v83
	v_max_f32_e32 v79, 0, v79
	v_max_f32_e32 v74, 0, v74
	v_max_f32_e32 v70, 0, v70
	v_max_f32_e32 v75, 0, v75
	v_max_f32_e32 v71, 0, v71
	v_mul_f32_e32 v80, v80, v80
	v_mul_f32_e32 v76, v76, v76
	v_mul_f32_e32 v81, v81, v81
	v_mul_f32_e32 v77, v77, v77
	v_mul_f32_e32 v82, v82, v82
	v_mul_f32_e32 v78, v78, v78
	v_mul_f32_e32 v83, v83, v83
	v_mul_f32_e32 v79, v79, v79
	v_mul_f32_e32 v74, v74, v74
	v_mul_f32_e32 v70, v70, v70
	v_mul_f32_e32 v75, v75, v75
	v_mul_f32_e32 v71, v71, v71
	v_max_f32_e32 v56, 0, v56
	v_max_f32_e32 v57, 0, v57
	v_max_f32_e32 v58, 0, v58
	s_mov_b32 s15, 0x200000
	v_max_f32_e32 v59, 0, v59
	v_max_f32_e32 v64, 0, v64
	v_max_f32_e32 v60, 0, v60
	v_max_f32_e32 v65, 0, v65
	v_max_f32_e32 v61, 0, v61
	v_max_f32_e32 v66, 0, v66
	v_max_f32_e32 v62, 0, v62
	v_max_f32_e32 v67, 0, v67
	v_max_f32_e32 v63, 0, v63
	v_max_f32_e32 v52, 0, v52
	v_max_f32_e32 v53, 0, v53
	v_max_f32_e32 v54, 0, v54
	v_max_f32_e32 v55, 0, v55
	v_mul_f32_e32 v64, v64, v64
	v_mul_f32_e32 v60, v60, v60
	s_waitcnt vmcnt(0)
	v_fmamk_f32 v100, v100, 0x3a000000, v232
	v_div_scale_f32 v104, s[26:27], v100, v100, 1.0
	v_rcp_f32_e32 v105, v104
	v_div_scale_f32 v84, vcc, 1.0, v100, 1.0
	v_mul_f32_e32 v65, v65, v65
	v_fma_f32 v85, -v104, v105, 1.0
	v_fmac_f32_e32 v105, v85, v105
	v_mul_f32_e32 v85, v84, v105
	v_fma_f32 v111, -v104, v85, v84
	v_fmac_f32_e32 v85, v111, v105
	v_fma_f32 v84, -v104, v85, v84
	v_div_fmas_f32 v84, v84, v105, v85
	v_div_fixup_f32 v84, v84, v100, 1.0
	v_mul_f32_e32 v85, v96, v84
	v_mul_f32_e32 v96, v102, v84
	v_mul_f32_e32 v97, v97, v84
	v_mul_f32_e32 v100, v103, v84
	v_mul_f32_e32 v98, v98, v84
	v_mul_f32_e32 v94, v94, v84
	v_mul_f32_e32 v99, v99, v84
	v_mul_f32_e32 v95, v95, v84
	v_mul_f32_e32 v101, v101, v84
	v_mul_f32_e32 v102, v106, v84
	v_mul_f32_e32 v103, v107, v84
	v_mul_f32_e32 v104, v108, v84
	v_mul_f32_e32 v105, v109, v84
	v_mul_f32_e32 v106, v86, v84
	v_mul_f32_e32 v107, v110, v84
	v_mul_f32_e32 v108, v87, v84
	v_cvt_pk_bf16_f32 v84, v85, v97
	v_cvt_pk_bf16_f32 v85, v98, v99
	v_cvt_pk_bf16_f32 v86, v96, v100
	v_cvt_pk_bf16_f32 v87, v94, v95
	global_store_dwordx4 v[92:93], v[84:87], off nt
	v_mul_f32_e32 v61, v61, v61
	v_mul_f32_e32 v66, v66, v66
	v_cvt_pk_bf16_f32 v84, v101, v103
	v_cvt_pk_bf16_f32 v85, v105, v107
	v_cvt_pk_bf16_f32 v86, v102, v104
	v_cvt_pk_bf16_f32 v87, v106, v108
	global_store_dwordx4 v[92:93], v[84:87], off offset:256 nt
	global_load_dword v84, v[90:91], off
	v_mul_f32_e32 v90, v69, v69
	v_mul_f32_e32 v86, v68, v68
	v_lshlrev_b64 v[68:69], 14, v[88:89]
	v_lshl_add_u64 v[68:69], s[8:9], 0, v[68:69]
	v_mul_f32_e32 v85, v72, v72
	v_mul_f32_e32 v87, v73, v73
	v_lshl_add_u64 v[72:73], v[68:69], 0, v[118:119]
	v_mul_f32_e32 v62, v62, v62
	v_mul_f32_e32 v67, v67, v67
	v_mul_f32_e32 v63, v63, v63
	v_mul_f32_e32 v52, v52, v52
	v_mul_f32_e32 v53, v53, v53
	v_mul_f32_e32 v54, v54, v54
	v_mul_f32_e32 v55, v55, v55
	v_max_f32_e32 v40, 0, v40
	v_max_f32_e32 v41, 0, v41
	v_max_f32_e32 v42, 0, v42
	v_max_f32_e32 v43, 0, v43
	v_max_f32_e32 v48, 0, v48
	v_max_f32_e32 v44, 0, v44
	v_max_f32_e32 v49, 0, v49
	v_max_f32_e32 v45, 0, v45
	v_max_f32_e32 v50, 0, v50
	v_max_f32_e32 v46, 0, v46
	v_max_f32_e32 v51, 0, v51
	v_max_f32_e32 v47, 0, v47
	v_max_f32_e32 v36, 0, v36
	v_max_f32_e32 v37, 0, v37
	v_max_f32_e32 v38, 0, v38
	v_max_f32_e32 v39, 0, v39
	v_mul_f32_e32 v48, v48, v48
	v_mul_f32_e32 v44, v44, v44
	v_mul_f32_e32 v49, v49, v49
	v_mul_f32_e32 v45, v45, v45
	v_mul_f32_e32 v50, v50, v50
	v_mul_f32_e32 v46, v46, v46
	v_mul_f32_e32 v51, v51, v51
	v_mul_f32_e32 v47, v47, v47
	v_mul_f32_e32 v36, v36, v36
	v_mul_f32_e32 v37, v37, v37
	v_mul_f32_e32 v38, v38, v38
	v_mul_f32_e32 v39, v39, v39
	v_max_f32_e32 v24, 0, v24
	v_max_f32_e32 v25, 0, v25
	v_max_f32_e32 v26, 0, v26
	v_max_f32_e32 v27, 0, v27
	v_max_f32_e32 v32, 0, v32
	s_waitcnt vmcnt(0)
; __device__ __forceinline__ unsigned cvt_pk_bf16(float lo, float hi) { unsigned r; asm volatile("v_cvt_pk_bf16_f32 %0, %1, %2" : "=v"(r) : "v"(lo), "v"(hi)); return r; }
;     __device__ __forceinline__ void operator()(const f32x4 (&acc)[2][2][4][2], const Unit& u, int wr, int wc, int fr, int fq) const {
;     ...
;             for (int m = 0; m < 4; ++m) { bf16_t* rowp = O + (size_t)(row0 + ai * HALF + m * 16) * ldc + col0;
;                 const float r2 = 1.0f / (rowsq[row0 + ai * HALF + m * 16] * (1.0f / 2048.0f) + 1e-6f);
; #pragma unroll
;                 for (int bj = 0; bj < 2; ++bj) { f32x4 v0 = acc[ai][bj][m][0], v1 = acc[ai][bj][m][1];
; #pragma unroll
;                     for (int j = 0; j < 4; ++j) { const float a = fmaxf(v0[j], 0.f), b = fmaxf(v1[j], 0.f); v0[j] = a * a * r2; v1[j] = b * b * r2; }
;                     u32x4 w; w.x = cvt_pk_bf16(v0[0], v0[1]); w.y = cvt_pk_bf16(v0[2], v0[3]); w.z = cvt_pk_bf16(v1[0], v1[1]); w.w = cvt_pk_bf16(v1[2], v1[3]);
;                     __builtin_nontemporal_store(w, (u32x4*)(rowp + bj * HALF)); } }
	v_fmamk_f32 v84, v84, 0x3a000000, v232
	v_div_scale_f32 v88, s[26:27], v84, v84, 1.0
	v_rcp_f32_e32 v89, v88
	v_div_scale_f32 v68, vcc, 1.0, v84, 1.0
	s_mov_b64 s[26:27], 0x200000
	v_fma_f32 v69, -v88, v89, 1.0
	v_fmac_f32_e32 v89, v69, v89
	v_mul_f32_e32 v69, v68, v89
	v_fma_f32 v91, -v88, v69, v68
	v_fmac_f32_e32 v69, v91, v89
	v_fma_f32 v68, -v88, v69, v68
	v_div_fmas_f32 v68, v68, v89, v69
	v_div_fixup_f32 v68, v68, v84, 1.0
	v_mul_f32_e32 v69, v80, v68
	v_mul_f32_e32 v76, v76, v68
	v_mul_f32_e32 v80, v81, v68
	v_mul_f32_e32 v77, v77, v68
	v_mul_f32_e32 v81, v82, v68
	v_mul_f32_e32 v78, v78, v68
	v_mul_f32_e32 v82, v83, v68
	v_mul_f32_e32 v79, v79, v68
	v_mul_f32_e32 v83, v85, v68
	v_mul_f32_e32 v84, v86, v68
	v_mul_f32_e32 v85, v87, v68
	v_mul_f32_e32 v86, v90, v68
	v_mul_f32_e32 v74, v74, v68
	v_mul_f32_e32 v87, v70, v68
	v_mul_f32_e32 v75, v75, v68
	v_mul_f32_e32 v88, v71, v68
	v_cvt_pk_bf16_f32 v68, v69, v80
	v_cvt_pk_bf16_f32 v69, v81, v82
	v_cvt_pk_bf16_f32 v70, v76, v77
	v_cvt_pk_bf16_f32 v71, v78, v79
	global_store_dwordx4 v[72:73], v[68:71], off nt
	v_max_f32_e32 v28, 0, v28
	v_max_f32_e32 v33, 0, v33
	v_cvt_pk_bf16_f32 v68, v83, v85
	v_cvt_pk_bf16_f32 v69, v74, v75
	v_cvt_pk_bf16_f32 v70, v84, v86
	v_cvt_pk_bf16_f32 v71, v87, v88
	global_store_dwordx4 v[72:73], v[68:71], off offset:256 nt
	global_load_dword v68, v[142:143], off offset:512
	v_mul_f32_e32 v72, v59, v59
	v_mul_f32_e32 v69, v56, v56
	v_mul_f32_e32 v70, v57, v57
	v_lshl_add_u64 v[56:57], v[116:117], 0, s[26:27]
	v_mul_f32_e32 v71, v58, v58
	v_add_co_u32_e32 v58, vcc, s15, v116
	s_mov_b32 s15, 0x240000
	s_nop 0
	v_addc_co_u32_e32 v59, vcc, 0, v117, vcc
	v_max_f32_e32 v29, 0, v29
	v_max_f32_e32 v34, 0, v34
	v_max_f32_e32 v30, 0, v30
	v_max_f32_e32 v35, 0, v35
	v_max_f32_e32 v31, 0, v31
	v_max_f32_e32 v20, 0, v20
	v_max_f32_e32 v21, 0, v21
	v_max_f32_e32 v22, 0, v22
	v_max_f32_e32 v23, 0, v23
	v_mul_f32_e32 v32, v32, v32
	v_mul_f32_e32 v28, v28, v28
	v_mul_f32_e32 v33, v33, v33
	v_mul_f32_e32 v29, v29, v29
	v_mul_f32_e32 v34, v34, v34
	v_mul_f32_e32 v30, v30, v30
	v_mul_f32_e32 v35, v35, v35
	v_mul_f32_e32 v31, v31, v31
	v_mul_f32_e32 v20, v20, v20
	v_mul_f32_e32 v21, v21, v21
	v_mul_f32_e32 v22, v22, v22
	v_mul_f32_e32 v23, v23, v23
	v_max_f32_e32 v8, 0, v8
	v_max_f32_e32 v9, 0, v9
	v_max_f32_e32 v10, 0, v10
	v_max_f32_e32 v11, 0, v11
	v_max_f32_e32 v16, 0, v16
	v_max_f32_e32 v12, 0, v12
	v_max_f32_e32 v17, 0, v17
	v_max_f32_e32 v13, 0, v13
	v_max_f32_e32 v18, 0, v18
	v_max_f32_e32 v14, 0, v14
	v_max_f32_e32 v19, 0, v19
	v_max_f32_e32 v15, 0, v15
	v_max_f32_e32 v4, 0, v4
	v_max_f32_e32 v5, 0, v5
	v_max_f32_e32 v6, 0, v6
	v_max_f32_e32 v7, 0, v7
	v_mul_f32_e32 v16, v16, v16
	v_mul_f32_e32 v12, v12, v12
	v_mul_f32_e32 v17, v17, v17
	v_mul_f32_e32 v13, v13, v13
	v_mul_f32_e32 v18, v18, v18
	v_mul_f32_e32 v14, v14, v14
	v_mul_f32_e32 v19, v19, v19
	v_mul_f32_e32 v15, v15, v15
	v_mul_f32_e32 v4, v4, v4
	v_mul_f32_e32 v5, v5, v5
	v_mul_f32_e32 v6, v6, v6
	v_mul_f32_e32 v7, v7, v7
	s_waitcnt vmcnt(0)
	v_fmamk_f32 v68, v68, 0x3a000000, v232
	v_div_scale_f32 v73, s[26:27], v68, v68, 1.0
	v_rcp_f32_e32 v74, v73
	v_div_scale_f32 v75, vcc, 1.0, v68, 1.0
	s_mov_b64 s[26:27], 0x240000
	v_fma_f32 v76, -v73, v74, 1.0
	v_fmac_f32_e32 v74, v76, v74
	v_mul_f32_e32 v76, v75, v74
	v_fma_f32 v77, -v73, v76, v75
	v_fmac_f32_e32 v76, v77, v74
	v_fma_f32 v73, -v73, v76, v75
	v_div_fmas_f32 v73, v73, v74, v76
	v_div_fixup_f32 v68, v73, v68, 1.0
	v_mul_f32_e32 v64, v64, v68
	v_mul_f32_e32 v60, v60, v68
	v_mul_f32_e32 v65, v65, v68
	v_mul_f32_e32 v61, v61, v68
	v_mul_f32_e32 v66, v66, v68
	v_mul_f32_e32 v62, v62, v68
	v_mul_f32_e32 v67, v67, v68
	v_mul_f32_e32 v63, v63, v68
	v_mul_f32_e32 v69, v69, v68
	v_mul_f32_e32 v73, v52, v68
	v_mul_f32_e32 v70, v70, v68
	v_mul_f32_e32 v74, v53, v68
	v_mul_f32_e32 v71, v71, v68
	v_mul_f32_e32 v75, v54, v68
	v_mul_f32_e32 v72, v72, v68
	v_mul_f32_e32 v68, v55, v68
	v_cvt_pk_bf16_f32 v52, v64, v65
	v_cvt_pk_bf16_f32 v53, v66, v67
	v_cvt_pk_bf16_f32 v54, v60, v61
	v_cvt_pk_bf16_f32 v55, v62, v63
	global_store_dwordx4 v[58:59], v[52:55], off nt
	s_nop 1
	v_cvt_pk_bf16_f32 v52, v69, v70
	v_cvt_pk_bf16_f32 v53, v71, v72
	v_cvt_pk_bf16_f32 v54, v73, v74
	v_cvt_pk_bf16_f32 v55, v75, v68
	global_store_dwordx4 v[56:57], v[52:55], off offset:256 nt
	global_load_dword v52, v[142:143], off offset:576
	v_mul_f32_e32 v56, v43, v43
	v_mul_f32_e32 v53, v40, v40
	v_mul_f32_e32 v54, v41, v41
	v_lshl_add_u64 v[40:41], v[116:117], 0, s[26:27]
	v_mul_f32_e32 v55, v42, v42
	v_add_co_u32_e32 v42, vcc, s15, v116
	s_mov_b32 s15, 0x280000
	s_nop 0
	v_addc_co_u32_e32 v43, vcc, 0, v117, vcc
	s_waitcnt vmcnt(0)
; __device__ __forceinline__ unsigned cvt_pk_bf16(float lo, float hi) { unsigned r; asm volatile("v_cvt_pk_bf16_f32 %0, %1, %2" : "=v"(r) : "v"(lo), "v"(hi)); return r; }
;     __device__ __forceinline__ void operator()(const f32x4 (&acc)[2][2][4][2], const Unit& u, int wr, int wc, int fr, int fq) const {
;     ...
;             for (int m = 0; m < 4; ++m) { bf16_t* rowp = O + (size_t)(row0 + ai * HALF + m * 16) * ldc + col0;
;                 const float r2 = 1.0f / (rowsq[row0 + ai * HALF + m * 16] * (1.0f / 2048.0f) + 1e-6f);
; #pragma unroll
;                 for (int bj = 0; bj < 2; ++bj) { f32x4 v0 = acc[ai][bj][m][0], v1 = acc[ai][bj][m][1];
; #pragma unroll
;                     for (int j = 0; j < 4; ++j) { const float a = fmaxf(v0[j], 0.f), b = fmaxf(v1[j], 0.f); v0[j] = a * a * r2; v1[j] = b * b * r2; }
;                     u32x4 w; w.x = cvt_pk_bf16(v0[0], v0[1]); w.y = cvt_pk_bf16(v0[2], v0[3]); w.z = cvt_pk_bf16(v1[0], v1[1]); w.w = cvt_pk_bf16(v1[2], v1[3]);
;                     __builtin_nontemporal_store(w, (u32x4*)(rowp + bj * HALF)); } }
	v_fmamk_f32 v52, v52, 0x3a000000, v232
	v_div_scale_f32 v57, s[26:27], v52, v52, 1.0
	v_rcp_f32_e32 v58, v57
	v_div_scale_f32 v59, vcc, 1.0, v52, 1.0
	s_mov_b64 s[26:27], 0x280000
	v_fma_f32 v60, -v57, v58, 1.0
	v_fmac_f32_e32 v58, v60, v58
	v_mul_f32_e32 v60, v59, v58
	v_fma_f32 v61, -v57, v60, v59
	v_fmac_f32_e32 v60, v61, v58
	v_fma_f32 v57, -v57, v60, v59
	v_div_fmas_f32 v57, v57, v58, v60
	v_div_fixup_f32 v52, v57, v52, 1.0
	v_mul_f32_e32 v48, v48, v52
	v_mul_f32_e32 v44, v44, v52
	v_mul_f32_e32 v49, v49, v52
	v_mul_f32_e32 v45, v45, v52
	v_mul_f32_e32 v50, v50, v52
	v_mul_f32_e32 v46, v46, v52
	v_mul_f32_e32 v51, v51, v52
	v_mul_f32_e32 v47, v47, v52
	v_mul_f32_e32 v53, v53, v52
	v_mul_f32_e32 v57, v36, v52
	v_mul_f32_e32 v54, v54, v52
	v_mul_f32_e32 v58, v37, v52
	v_mul_f32_e32 v55, v55, v52
	v_mul_f32_e32 v59, v38, v52
	v_mul_f32_e32 v56, v56, v52
	v_mul_f32_e32 v52, v39, v52
	v_cvt_pk_bf16_f32 v36, v48, v49
	v_cvt_pk_bf16_f32 v37, v50, v51
	v_cvt_pk_bf16_f32 v38, v44, v45
	v_cvt_pk_bf16_f32 v39, v46, v47
	global_store_dwordx4 v[42:43], v[36:39], off nt
	s_nop 1
	v_cvt_pk_bf16_f32 v36, v53, v54
	v_cvt_pk_bf16_f32 v37, v55, v56
	v_cvt_pk_bf16_f32 v38, v57, v58
	v_cvt_pk_bf16_f32 v39, v59, v52
	global_store_dwordx4 v[40:41], v[36:39], off offset:256 nt
	global_load_dword v36, v[142:143], off offset:640
	v_mul_f32_e32 v40, v27, v27
	v_mul_f32_e32 v37, v24, v24
	v_mul_f32_e32 v38, v25, v25
	v_lshl_add_u64 v[24:25], v[116:117], 0, s[26:27]
	v_mul_f32_e32 v39, v26, v26
	v_add_co_u32_e32 v26, vcc, s15, v116
	s_mov_b32 s15, 0x2c0000
	s_nop 0
	v_addc_co_u32_e32 v27, vcc, 0, v117, vcc
	s_waitcnt vmcnt(0)
	v_fmamk_f32 v36, v36, 0x3a000000, v232
	v_div_scale_f32 v41, s[26:27], v36, v36, 1.0
	v_rcp_f32_e32 v42, v41
	v_div_scale_f32 v43, vcc, 1.0, v36, 1.0
	s_mov_b64 s[26:27], 0x2c0000
	v_fma_f32 v44, -v41, v42, 1.0
	v_fmac_f32_e32 v42, v44, v42
	v_mul_f32_e32 v44, v43, v42
	v_fma_f32 v45, -v41, v44, v43
	v_fmac_f32_e32 v44, v45, v42
	v_fma_f32 v41, -v41, v44, v43
	v_div_fmas_f32 v41, v41, v42, v44
	v_div_fixup_f32 v36, v41, v36, 1.0
	v_mul_f32_e32 v32, v32, v36
	v_mul_f32_e32 v28, v28, v36
	v_mul_f32_e32 v33, v33, v36
	v_mul_f32_e32 v29, v29, v36
	v_mul_f32_e32 v34, v34, v36
	v_mul_f32_e32 v30, v30, v36
	v_mul_f32_e32 v35, v35, v36
	v_mul_f32_e32 v31, v31, v36
	v_mul_f32_e32 v37, v37, v36
	v_mul_f32_e32 v41, v20, v36
	v_mul_f32_e32 v38, v38, v36
	v_mul_f32_e32 v42, v21, v36
	v_mul_f32_e32 v39, v39, v36
	v_mul_f32_e32 v43, v22, v36
	v_mul_f32_e32 v40, v40, v36
	v_mul_f32_e32 v36, v23, v36
	v_cvt_pk_bf16_f32 v20, v32, v33
	v_cvt_pk_bf16_f32 v21, v34, v35
	v_cvt_pk_bf16_f32 v22, v28, v29
	v_cvt_pk_bf16_f32 v23, v30, v31
	global_store_dwordx4 v[26:27], v[20:23], off nt
	s_nop 1
	v_cvt_pk_bf16_f32 v20, v37, v38
	v_cvt_pk_bf16_f32 v21, v39, v40
	v_cvt_pk_bf16_f32 v22, v41, v42
	v_cvt_pk_bf16_f32 v23, v43, v36
	global_store_dwordx4 v[24:25], v[20:23], off offset:256 nt
	global_load_dword v20, v[142:143], off offset:704
	v_mul_f32_e32 v24, v11, v11
	v_mul_f32_e32 v21, v8, v8
	v_mul_f32_e32 v22, v9, v9
	v_lshl_add_u64 v[8:9], v[116:117], 0, s[26:27]
	v_mul_f32_e32 v23, v10, v10
	v_add_co_u32_e32 v10, vcc, s15, v116
	s_waitcnt vmcnt(0)
	v_fmamk_f32 v20, v20, 0x3a000000, v232
	v_div_scale_f32 v25, s[26:27], v20, v20, 1.0
	v_rcp_f32_e32 v26, v25
	v_addc_co_u32_e32 v11, vcc, 0, v117, vcc
	v_div_scale_f32 v27, vcc, 1.0, v20, 1.0
	v_fma_f32 v28, -v25, v26, 1.0
	v_fmac_f32_e32 v26, v28, v26
	v_mul_f32_e32 v28, v27, v26
	v_fma_f32 v29, -v25, v28, v27
	v_fmac_f32_e32 v28, v29, v26
	v_fma_f32 v25, -v25, v28, v27
	v_div_fmas_f32 v25, v25, v26, v28
	v_div_fixup_f32 v20, v25, v20, 1.0
	s_andn2_b64 vcc, exec, s[4:5]
	v_mul_f32_e32 v16, v16, v20
	v_mul_f32_e32 v12, v12, v20
	v_mul_f32_e32 v17, v17, v20
	v_mul_f32_e32 v13, v13, v20
	v_mul_f32_e32 v18, v18, v20
	v_mul_f32_e32 v14, v14, v20
	v_mul_f32_e32 v19, v19, v20
	v_mul_f32_e32 v15, v15, v20
	v_mul_f32_e32 v21, v21, v20
	v_mul_f32_e32 v25, v4, v20
	v_mul_f32_e32 v22, v22, v20
	v_mul_f32_e32 v26, v5, v20
	v_mul_f32_e32 v23, v23, v20
	v_mul_f32_e32 v27, v6, v20
	v_mul_f32_e32 v24, v24, v20
	v_mul_f32_e32 v20, v7, v20
	v_cvt_pk_bf16_f32 v4, v16, v17
	v_cvt_pk_bf16_f32 v5, v18, v19
	v_cvt_pk_bf16_f32 v6, v12, v13
	v_cvt_pk_bf16_f32 v7, v14, v15
	s_mov_b64 s[4:5], -1
	global_store_dwordx4 v[10:11], v[4:7], off nt
	s_nop 1
	v_cvt_pk_bf16_f32 v4, v21, v22
	v_cvt_pk_bf16_f32 v5, v23, v24
	v_cvt_pk_bf16_f32 v6, v25, v26
	v_cvt_pk_bf16_f32 v7, v27, v20
	global_store_dwordx4 v[8:9], v[4:7], off offset:256 nt
	s_cbranch_vccnz .LBB0_2096
	s_andn2_b64 vcc, exec, s[6:7]
	s_cbranch_vccnz .LBB0_2095
	s_barrier
	s_branch .LBB0_2095
